# MLA-up K/V part: the two accumulators of a wave exchanged across half-waves (v_permlane32_swap) so each 2-byte store instruction writes one row x 128 contiguous bytes (was 2 rows x 64 bytes)
# speedup vs baseline: 1.0003x; 1.0003x over previous
; DI unsigned pk2(float lo, float hi) { f32x2 v = {lo, hi}; b16x2 r = __builtin_convertvector(v, b16x2); return __builtin_bit_cast(unsigned, r); }
; DI void phase_mla_up(const Params& p, int layer, char* lds) {
;     ...
;           const int head = c0 >> 7, within = c0 & 127;
;           const size_t hrow = (size_t)(bq * 6 + head) * S + srow;
;           if (within < 64) {
;             u16* kp = KB + hrow * 96 + within + l32;
; #pragma unroll
;             for (int r = 0; r < 16; ++r) kp[((r & 3) + 8 * (r >> 2)) * 96] = (u16)(pk2(acc[r] * rv[r], 0.f) & 0xffffu);
;           } else {
;             u16* vp = VB + hrow * 64 + (within - 64) + l32;
; #pragma unroll
;             for (int r = 0; r < 16; ++r) vp[((r & 3) + 8 * (r >> 2)) * 64] = (u16)(pk2(acc[r] * rv[r], 0.f) & 0xffffu);
;           }
.LBB0_222:
	s_mov_b64 s[12:13], -1
	s_and_b64 vcc, exec, s[20:21]
	s_cbranch_vccz .LBB0_228
	v_ashrrev_i32_e32 v4, 7, v78
	v_add_u32_e32 v80, s28, v4
	v_ashrrev_i32_e32 v81, 31, v80
	v_lshlrev_b64 v[80:81], 13, v[80:81]
	v_or_b32_e32 v80, v80, v72
	s_and_saveexec_b64 s[12:13], s[6:7]
	s_xor_b64 s[12:13], exec, s[12:13]
	s_cbranch_execz .LBB0_225
	v_lshlrev_b64 v[80:81], 7, v[80:81]
	v_mul_f32_e32 v4, v95, v22
	v_mul_f32_e32 v238, v95, v6
	v_lshl_add_u64 v[80:81], v[66:67], 0, v[80:81]
	v_bfe_u32 v239, v184, 5, 1
	v_mul_i32_i24_e32 v124, -448, v239
	v_ashrrev_i32_e32 v125, 31, v124
	v_lshl_add_u64 v[116:117], v[80:81], 0, v[124:125]
	v_mov_b32_e32 v124, 512
	v_mov_b32_e32 v125, 0
	v_lshl_add_u64 v[118:119], v[116:117], 0, v[124:125]
	v_cvt_pk_bf16_f32 v4, v4, s0
	v_cvt_pk_bf16_f32 v238, v238, s0
	s_nop 1
	v_permlane32_swap_b32_e32 v4, v238
	global_store_short v[116:117], v4, off offset:-128
	global_store_short v[118:119], v238, off offset:-128
	v_mul_f32_e32 v4, v96, v23
	v_mul_f32_e32 v238, v96, v7
	v_cvt_pk_bf16_f32 v4, v4, s0
	v_cvt_pk_bf16_f32 v238, v238, s0
	s_nop 1
	v_permlane32_swap_b32_e32 v4, v238
	global_store_short v[116:117], v4, off
	global_store_short v[118:119], v238, off
	v_mul_f32_e32 v4, v97, v24
	v_mul_f32_e32 v238, v97, v8
	v_cvt_pk_bf16_f32 v4, v4, s0
	v_cvt_pk_bf16_f32 v238, v238, s0
	s_nop 1
	v_permlane32_swap_b32_e32 v4, v238
	global_store_short v[116:117], v4, off offset:128
	global_store_short v[118:119], v238, off offset:128
	v_mul_f32_e32 v4, v98, v25
	v_mul_f32_e32 v238, v98, v9
	v_cvt_pk_bf16_f32 v4, v4, s0
	v_cvt_pk_bf16_f32 v238, v238, s0
	s_nop 1
	v_permlane32_swap_b32_e32 v4, v238
	global_store_short v[116:117], v4, off offset:256
	global_store_short v[118:119], v238, off offset:256
	v_mul_f32_e32 v4, v99, v26
	v_mul_f32_e32 v238, v99, v10
	v_cvt_pk_bf16_f32 v4, v4, s0
	v_cvt_pk_bf16_f32 v238, v238, s0
	s_nop 1
	v_permlane32_swap_b32_e32 v4, v238
	global_store_short v[116:117], v4, off offset:896
	global_store_short v[118:119], v238, off offset:896
	v_mul_f32_e32 v4, v100, v27
	v_mul_f32_e32 v238, v100, v11
	v_cvt_pk_bf16_f32 v4, v4, s0
	v_cvt_pk_bf16_f32 v238, v238, s0
	s_nop 1
	v_permlane32_swap_b32_e32 v4, v238
	global_store_short v[116:117], v4, off offset:1024
	global_store_short v[118:119], v238, off offset:1024
	v_mul_f32_e32 v4, v101, v28
	v_mul_f32_e32 v238, v101, v12
	v_cvt_pk_bf16_f32 v4, v4, s0
	v_cvt_pk_bf16_f32 v238, v238, s0
	s_nop 1
	v_permlane32_swap_b32_e32 v4, v238
	global_store_short v[116:117], v4, off offset:1152
	global_store_short v[118:119], v238, off offset:1152
	v_mul_f32_e32 v4, v102, v29
	v_mul_f32_e32 v238, v102, v13
	v_cvt_pk_bf16_f32 v4, v4, s0
	v_cvt_pk_bf16_f32 v238, v238, s0
	s_nop 1
	v_permlane32_swap_b32_e32 v4, v238
	global_store_short v[116:117], v4, off offset:1280
	global_store_short v[118:119], v238, off offset:1280
	v_mul_f32_e32 v4, v103, v30
	v_mul_f32_e32 v238, v103, v14
	v_cvt_pk_bf16_f32 v4, v4, s0
	v_cvt_pk_bf16_f32 v238, v238, s0
	s_nop 1
	v_permlane32_swap_b32_e32 v4, v238
	global_store_short v[116:117], v4, off offset:1920
	global_store_short v[118:119], v238, off offset:1920
	v_mul_f32_e32 v4, v104, v31
	v_mul_f32_e32 v238, v104, v15
	v_cvt_pk_bf16_f32 v4, v4, s0
	v_cvt_pk_bf16_f32 v238, v238, s0
	s_nop 1
	v_permlane32_swap_b32_e32 v4, v238
	global_store_short v[116:117], v4, off offset:2048
	global_store_short v[118:119], v238, off offset:2048
	v_mul_f32_e32 v4, v105, v32
	v_mul_f32_e32 v238, v105, v16
	v_cvt_pk_bf16_f32 v4, v4, s0
	v_cvt_pk_bf16_f32 v238, v238, s0
	s_nop 1
	v_permlane32_swap_b32_e32 v4, v238
	global_store_short v[116:117], v4, off offset:2176
	global_store_short v[118:119], v238, off offset:2176
	v_mul_f32_e32 v4, v106, v33
	v_mul_f32_e32 v238, v106, v17
	v_cvt_pk_bf16_f32 v4, v4, s0
	v_cvt_pk_bf16_f32 v238, v238, s0
	s_nop 1
	v_permlane32_swap_b32_e32 v4, v238
	global_store_short v[116:117], v4, off offset:2304
	global_store_short v[118:119], v238, off offset:2304
	v_mul_f32_e32 v4, v107, v34
	v_mul_f32_e32 v238, v107, v18
	v_cvt_pk_bf16_f32 v4, v4, s0
	v_cvt_pk_bf16_f32 v238, v238, s0
	s_nop 1
	v_permlane32_swap_b32_e32 v4, v238
	global_store_short v[116:117], v4, off offset:2944
	global_store_short v[118:119], v238, off offset:2944
	v_mul_f32_e32 v4, v108, v35
	v_mul_f32_e32 v238, v108, v19
	v_cvt_pk_bf16_f32 v4, v4, s0
	v_cvt_pk_bf16_f32 v238, v238, s0
	s_nop 1
	v_permlane32_swap_b32_e32 v4, v238
	global_store_short v[116:117], v4, off offset:3072
	global_store_short v[118:119], v238, off offset:3072
	v_mul_f32_e32 v4, v109, v36
	v_mul_f32_e32 v238, v109, v20
	v_cvt_pk_bf16_f32 v4, v4, s0
	v_cvt_pk_bf16_f32 v238, v238, s0
	s_nop 1
	v_permlane32_swap_b32_e32 v4, v238
	global_store_short v[116:117], v4, off offset:3200
	global_store_short v[118:119], v238, off offset:3200
	v_mul_f32_e32 v4, v110, v37
	v_mul_f32_e32 v238, v110, v21
	v_cvt_pk_bf16_f32 v4, v4, s0
	v_cvt_pk_bf16_f32 v238, v238, s0
	s_nop 1
	v_permlane32_swap_b32_e32 v4, v238
	global_store_short v[116:117], v4, off offset:3328
	global_store_short v[118:119], v238, off offset:3328
; DI unsigned pk2(float lo, float hi) { f32x2 v = {lo, hi}; b16x2 r = __builtin_convertvector(v, b16x2); return __builtin_bit_cast(unsigned, r); }
; DI void phase_mla_up(const Params& p, int layer, char* lds) {
;     ...
;           const int head = c0 >> 7, within = c0 & 127;
;           const size_t hrow = (size_t)(bq * 6 + head) * S + srow;
;           if (within < 64) {
;             u16* kp = KB + hrow * 96 + within + l32;
; #pragma unroll
;             for (int r = 0; r < 16; ++r) kp[((r & 3) + 8 * (r >> 2)) * 96] = (u16)(pk2(acc[r] * rv[r], 0.f) & 0xffffu);
.LBB0_225:
	s_andn2_saveexec_b64 s[12:13], s[12:13]
	s_cbranch_execz .LBB0_227
	v_mad_u64_u32 v[112:113], s[54:55], v80, s33, v[60:61]
	v_mul_f32_e32 v4, v95, v22
	v_mul_f32_e32 v238, v95, v6
	v_mad_i32_i24 v113, v81, s33, v113
	v_bfe_u32 v239, v184, 5, 1
	v_mul_i32_i24_e32 v124, -704, v239
	v_ashrrev_i32_e32 v125, 31, v124
	v_lshl_add_u64 v[116:117], v[112:113], 0, v[124:125]
	v_mov_b32_e32 v124, 768
	v_mov_b32_e32 v125, 0
	v_lshl_add_u64 v[118:119], v[116:117], 0, v[124:125]
	v_cvt_pk_bf16_f32 v4, v4, s0
	v_cvt_pk_bf16_f32 v238, v238, s0
	s_nop 1
	v_permlane32_swap_b32_e32 v4, v238
	global_store_short v[116:117], v4, off
	global_store_short v[118:119], v238, off
	v_mul_f32_e32 v4, v96, v23
	v_mul_f32_e32 v238, v96, v7
	v_cvt_pk_bf16_f32 v4, v4, s0
	v_cvt_pk_bf16_f32 v238, v238, s0
	s_nop 1
	v_permlane32_swap_b32_e32 v4, v238
	global_store_short v[116:117], v4, off offset:192
	global_store_short v[118:119], v238, off offset:192
	v_mul_f32_e32 v4, v97, v24
	v_mul_f32_e32 v238, v97, v8
	v_cvt_pk_bf16_f32 v4, v4, s0
	v_cvt_pk_bf16_f32 v238, v238, s0
	s_nop 1
	v_permlane32_swap_b32_e32 v4, v238
	global_store_short v[116:117], v4, off offset:384
	global_store_short v[118:119], v238, off offset:384
	v_mul_f32_e32 v4, v98, v25
	v_mul_f32_e32 v238, v98, v9
	v_cvt_pk_bf16_f32 v4, v4, s0
	v_cvt_pk_bf16_f32 v238, v238, s0
	s_nop 1
	v_permlane32_swap_b32_e32 v4, v238
	global_store_short v[116:117], v4, off offset:576
	global_store_short v[118:119], v238, off offset:576
	v_mul_f32_e32 v4, v99, v26
	v_mul_f32_e32 v238, v99, v10
	v_cvt_pk_bf16_f32 v4, v4, s0
	v_cvt_pk_bf16_f32 v238, v238, s0
	s_nop 1
	v_permlane32_swap_b32_e32 v4, v238
	global_store_short v[116:117], v4, off offset:1536
	global_store_short v[118:119], v238, off offset:1536
	v_mul_f32_e32 v4, v100, v27
	v_mul_f32_e32 v238, v100, v11
	v_cvt_pk_bf16_f32 v4, v4, s0
	v_cvt_pk_bf16_f32 v238, v238, s0
	s_nop 1
	v_permlane32_swap_b32_e32 v4, v238
	global_store_short v[116:117], v4, off offset:1728
	global_store_short v[118:119], v238, off offset:1728
	v_mul_f32_e32 v4, v101, v28
	v_mul_f32_e32 v238, v101, v12
	v_cvt_pk_bf16_f32 v4, v4, s0
	v_cvt_pk_bf16_f32 v238, v238, s0
	s_nop 1
	v_permlane32_swap_b32_e32 v4, v238
	global_store_short v[116:117], v4, off offset:1920
	global_store_short v[118:119], v238, off offset:1920
	v_mul_f32_e32 v4, v102, v29
	v_mul_f32_e32 v238, v102, v13
	v_cvt_pk_bf16_f32 v4, v4, s0
	v_cvt_pk_bf16_f32 v238, v238, s0
	s_nop 1
	v_permlane32_swap_b32_e32 v4, v238
	global_store_short v[116:117], v4, off offset:2112
	global_store_short v[118:119], v238, off offset:2112
	v_mul_f32_e32 v4, v103, v30
	v_mul_f32_e32 v238, v103, v14
	v_cvt_pk_bf16_f32 v4, v4, s0
	v_cvt_pk_bf16_f32 v238, v238, s0
	s_nop 1
	v_permlane32_swap_b32_e32 v4, v238
	global_store_short v[116:117], v4, off offset:3072
	global_store_short v[118:119], v238, off offset:3072
	v_mul_f32_e32 v4, v104, v31
	v_mul_f32_e32 v238, v104, v15
	v_cvt_pk_bf16_f32 v4, v4, s0
	v_cvt_pk_bf16_f32 v238, v238, s0
	s_nop 1
	v_permlane32_swap_b32_e32 v4, v238
	global_store_short v[116:117], v4, off offset:3264
	global_store_short v[118:119], v238, off offset:3264
	v_mul_f32_e32 v4, v105, v32
	v_mul_f32_e32 v238, v105, v16
	v_cvt_pk_bf16_f32 v4, v4, s0
	v_cvt_pk_bf16_f32 v238, v238, s0
	s_nop 1
	v_permlane32_swap_b32_e32 v4, v238
	global_store_short v[116:117], v4, off offset:3456
	global_store_short v[118:119], v238, off offset:3456
	v_mul_f32_e32 v4, v106, v33
	v_mul_f32_e32 v238, v106, v17
	v_cvt_pk_bf16_f32 v4, v4, s0
	v_cvt_pk_bf16_f32 v238, v238, s0
	s_nop 1
	v_permlane32_swap_b32_e32 v4, v238
	global_store_short v[116:117], v4, off offset:3648
	global_store_short v[118:119], v238, off offset:3648
	v_mul_f32_e32 v4, v107, v34
	v_mul_f32_e32 v238, v107, v18
	v_add_co_u32_e32 v80, vcc, s48, v112
	v_cvt_pk_bf16_f32 v4, v4, s0
	s_nop 0
	v_addc_co_u32_e32 v81, vcc, 0, v113, vcc
	v_mov_b32_e32 v124, s48
	v_mov_b32_e32 v125, 0
	v_lshl_add_u64 v[120:121], v[116:117], 0, v[124:125]
	v_lshl_add_u64 v[122:123], v[118:119], 0, v[124:125]
	v_cvt_pk_bf16_f32 v238, v238, s0
	s_nop 1
	v_permlane32_swap_b32_e32 v4, v238
	global_store_short v[120:121], v4, off offset:512
	global_store_short v[122:123], v238, off offset:512
	v_mul_f32_e32 v4, v108, v35
	v_mul_f32_e32 v238, v108, v19
	v_cvt_pk_bf16_f32 v4, v4, s0
	v_cvt_pk_bf16_f32 v238, v238, s0
	s_nop 1
	v_permlane32_swap_b32_e32 v4, v238
	global_store_short v[120:121], v4, off offset:704
	global_store_short v[122:123], v238, off offset:704
	v_mul_f32_e32 v4, v109, v36
	v_mul_f32_e32 v238, v109, v20
	v_cvt_pk_bf16_f32 v4, v4, s0
	v_cvt_pk_bf16_f32 v238, v238, s0
	s_nop 1
	v_permlane32_swap_b32_e32 v4, v238
	global_store_short v[120:121], v4, off offset:896
	global_store_short v[122:123], v238, off offset:896
	v_mul_f32_e32 v4, v110, v37
	v_mul_f32_e32 v238, v110, v21
	v_cvt_pk_bf16_f32 v4, v4, s0
	v_cvt_pk_bf16_f32 v238, v238, s0
	s_nop 1
	v_permlane32_swap_b32_e32 v4, v238
	global_store_short v[120:121], v4, off offset:1088
	global_store_short v[122:123], v238, off offset:1088

; DI void phase_mla_up(const Params& p, int layer, char* lds) {
;     ...
;         if (c0 < NOUT) epi(acc0, c0);
;         if (c0 + 32 < NOUT) epi(acc1, c0 + 32);
.LBB0_262:
	s_or_b64 exec, exec, s[26:27]
	s_nop 2
	v_add_u32_e32 v26, 32, v78
	v_cmp_gt_i32_e32 vcc, s73, v26
	s_and_saveexec_b64 s[26:27], vcc
	s_cbranch_execz .LBB0_190
	s_mov_b64 s[12:13], -1
	s_and_b64 vcc, exec, s[20:21]
	s_cbranch_vccz .LBB0_269
	s_mov_b64 s[12:13], 0
	s_branch .LBB0_269
	v_ashrrev_i32_e32 v4, 7, v78
	v_add_u32_e32 v22, s28, v4
	v_ashrrev_i32_e32 v23, 31, v22
	v_and_b32_e32 v27, 0x60, v26
	v_lshlrev_b64 v[24:25], 13, v[22:23]
	v_or_b32_e32 v24, v24, v72
	v_cmp_lt_u32_e32 vcc, 63, v27
	v_lshlrev_b32_e32 v4, 1, v27
	v_lshlrev_b32_e32 v22, 1, v58
	s_and_saveexec_b64 s[12:13], vcc
	s_xor_b64 s[12:13], exec, s[12:13]
	s_cbranch_execz .LBB0_266
	v_lshlrev_b64 v[24:25], 7, v[24:25]
	v_lshl_add_u64 v[24:25], s[68:69], 0, v[24:25]
	v_lshl_add_u64 v[24:25], v[24:25], 0, v[4:5]
	v_mov_b32_e32 v23, v5
	v_mul_f32_e32 v4, v95, v6
	v_lshl_add_u64 v[22:23], v[24:25], 0, v[22:23]
	v_cvt_pk_bf16_f32 v4, v4, s0
	global_store_short v[22:23], v4, off offset:-128
	v_mul_f32_e32 v4, v96, v7
	v_cvt_pk_bf16_f32 v4, v4, s0
	global_store_short v[22:23], v4, off
	v_mul_f32_e32 v4, v97, v8
	v_cvt_pk_bf16_f32 v4, v4, s0
	global_store_short v[22:23], v4, off offset:128
	v_mul_f32_e32 v4, v98, v9
	v_cvt_pk_bf16_f32 v4, v4, s0
	global_store_short v[22:23], v4, off offset:256
	v_mul_f32_e32 v4, v99, v10
	v_cvt_pk_bf16_f32 v4, v4, s0
	global_store_short v[22:23], v4, off offset:896
	v_mul_f32_e32 v4, v100, v11
	v_cvt_pk_bf16_f32 v4, v4, s0
	global_store_short v[22:23], v4, off offset:1024
	v_mul_f32_e32 v4, v101, v12
	v_cvt_pk_bf16_f32 v4, v4, s0
	global_store_short v[22:23], v4, off offset:1152
	v_mul_f32_e32 v4, v102, v13
	v_cvt_pk_bf16_f32 v4, v4, s0
	global_store_short v[22:23], v4, off offset:1280
	v_mul_f32_e32 v4, v103, v14
	v_cvt_pk_bf16_f32 v4, v4, s0
	global_store_short v[22:23], v4, off offset:1920
	v_mul_f32_e32 v4, v104, v15
	v_cvt_pk_bf16_f32 v4, v4, s0
	global_store_short v[22:23], v4, off offset:2048
	v_mul_f32_e32 v4, v105, v16
	v_cvt_pk_bf16_f32 v4, v4, s0
	global_store_short v[22:23], v4, off offset:2176
	v_mul_f32_e32 v4, v106, v17
	v_cvt_pk_bf16_f32 v4, v4, s0
	global_store_short v[22:23], v4, off offset:2304
	v_mul_f32_e32 v4, v107, v18
	v_cvt_pk_bf16_f32 v4, v4, s0
	global_store_short v[22:23], v4, off offset:2944
	v_mul_f32_e32 v4, v108, v19
	v_cvt_pk_bf16_f32 v4, v4, s0
	global_store_short v[22:23], v4, off offset:3072
	v_mul_f32_e32 v4, v109, v20
	v_cvt_pk_bf16_f32 v4, v4, s0
	global_store_short v[22:23], v4, off offset:3200
	v_mul_f32_e32 v4, v110, v21
	v_cvt_pk_bf16_f32 v4, v4, s0
	global_store_short v[22:23], v4, off offset:3328
